# compact MFMA-ordered copy of the DSA index keys (written by inproj epilogue into the idle mm region); level-0 and collect passes read it as contiguous 1-KB wave loads
# baseline (speedup 1.0000x reference)
;   __device__ __forceinline__ const float* x() const { return (const float*)(const __attribute__((address_space(1))) float*)kp[0]; }
;   __device__ __forceinline__ half_t* xh() const { return (half_t*)(ws() + OFF_xh); }
;   __device__ __forceinline__ half_t* winT() const { return (half_t*)(ws() + OFF_winT); }
;   __device__ __forceinline__ half_t* vsT() const { return (half_t*)(ws() + OFF_vsT); }
;   __device__ __forceinline__ half_t* vwT() const { return (half_t*)(ws() + OFF_vwT); }
; __device__ __forceinline__ void phase_inproj(const KP& p, int l, char* smem, int* q, int xcc) {
;     ...
;   xcd_schedule(q, xcc, 128, 32, smem, [&](int grp, int within) __attribute__((always_inline)) {
;     const int mt = (grp & 15) * 4 + (within & 3), nt = (grp >> 4) * 8 + (within >> 2);
;     if (nt >= 58) return;
;     const int m0 = mt * 256, n0 = nt * 128;
;     const half_t* A = p.xh() + (size_t)m0 * DM;
;     const half_t* B = p.winT() + (size_t)n0 * DM;
;     int tidx = threadIdx.x;
;     asm volatile("" : "+v"(tidx));
;     const int lane = tidx & 63, wn = (tidx >> 6) & 1;
;     float bv[2];
; #pragma unroll
;     for (int ni = 0; ni < 2; ++ni) {
;       const int oc = orig_col(n0 + wn * 64 + ni * 32 + (lane & 31));
;       bv[ni] = oc >= 0 ? bias[oc] : 0.f;
;     }
;     half_t* vT = (nt == 53) ? p.vsT() : ((nt == 55) ? p.vwT() : nullptr);
.LBB0_197:
	s_andn2_b64 vcc, exec, s[2:3]
	s_cbranch_vccnz .LBB0_188
	s_lshl_b32 s53, s15, 5
	s_sub_i32 s43, s14, s53
	s_lshl_b32 s2, s15, 2
	s_and_b32 s38, s2, -8
	s_ashr_i32 s2, s43, 2
	s_add_i32 s38, s38, s2
	s_cmp_gt_i32 s38, 57
	s_cbranch_scc1 .LBB0_188
	s_cmp_eq_u32 s38, 57
	s_cselect_b32 s2, 1, 0
	v_writelane_b32 v251, s2, 22
	v_mov_b32_e32 v0, v224
	s_lshl_b32 s18, s38, 7
	v_and_b32_e32 v0, 0x5f, v0
	v_or_b32_e32 v2, s18, v0
	s_ashr_i32 s19, s18, 31
	v_cmp_lt_i32_e32 vcc, s60, v2
	v_mov_b32_e32 v0, v2
	s_and_saveexec_b64 s[2:3], vcc
	s_cbranch_execz .LBB0_236
	s_cmpk_gt_u32 s18, 0x7ff
	s_mov_b64 s[14:15], -1
	s_cbranch_scc0 .LBB0_234
	s_cmpk_gt_u32 s18, 0x9ff
	s_cbranch_scc0 .LBB0_231
	s_cmpk_gt_u32 s18, 0xbff
	s_cbranch_scc0 .LBB0_228
	s_cmpk_gt_u32 s18, 0x17ff
	s_cbranch_scc0 .LBB0_225
	s_cmpk_gt_u32 s18, 0x18ff
	s_cbranch_scc0 .LBB0_222
	s_cmpk_gt_u32 s18, 0x1bff
	s_cbranch_scc0 .LBB0_219
	s_cmpk_gt_u32 s18, 0x1c7f
	s_cbranch_scc0 .LBB0_216
	s_movk_i32 s14, 0x1c9f
	v_cmp_lt_u32_e32 vcc, s14, v2
	s_and_saveexec_b64 s[14:15], vcc
	s_xor_b64 s[30:31], exec, s[14:15]
	s_cbranch_execz .LBB0_213
	s_movk_i32 s14, 0x1ca7
	v_cmp_lt_u32_e32 vcc, s14, v2
	s_and_saveexec_b64 s[14:15], vcc
	s_xor_b64 s[14:15], exec, s[14:15]
	s_movk_i32 s39, 0x1cc0
	v_add_u32_e32 v0, 0xfffff200, v2
	v_cmp_gt_u32_e32 vcc, s39, v2
	s_nop 1
	v_cndmask_b32_e32 v0, -1, v0, vcc
	s_andn2_saveexec_b64 s[14:15], s[14:15]
	v_add_u32_e32 v0, 0xffffed00, v2
	s_or_b64 exec, exec, s[14:15]

;   __device__ __forceinline__ half_t* u() const { return (half_t*)(ws() + OFF_u); }
; __device__ __forceinline__ void phase_inproj(const KP& p, int l, char* smem, int* q, int xcc) {
;     ...
;     gemm_tile_big(
;         DM, [&](int r, int k) { return *(const uint4*)(A + (size_t)r * DM + k); },
;         [&](int r, int k) { return *(const uint4*)(B + (size_t)r * DM + k); },
;         [&](int mi, int ni, int r, int row, int col, float v) {
;           const half_t hv = (half_t)(v + bv[ni]);
;           const int tok = m0 + row;
;           p.u()[(size_t)tok * NU + n0 + col] = hv;
;           if (vT) {
;             const int b = tok >> 13, t = tok & 8191;
;             vT[((size_t)(b * 2 + (col >> 6)) * 64 + (col & 63)) * SEQ + t] = hv;
;           }
;         },
;         smem);
.Lip_novt:
	v_readlane_b32 s2, v251, 22
	v_readfirstlane_b32 s3, v224
	s_nop 3
	s_cmp_eq_u32 s2, 0
	s_cbranch_scc1 .Lip_noik
	s_bitcmp1_b32 s3, 6
	s_cbranch_scc1 .Lip_noik
	v_and_b32_e32 v135, 31, v224
	v_lshrrev_b32_e32 v135, 3, v135
	v_lshlrev_b32_e32 v135, 8, v135
	v_and_b32_e32 v136, 7, v224
	v_lshl_add_u32 v135, v136, 1, v135
	v_bfe_u32 v136, v224, 5, 1
	v_lshl_add_u32 v135, v136, 6, v135
	v_lshrrev_b32_e32 v136, 7, v224
	v_lshl_add_u32 v135, v136, 13, v135
	s_lshl_b32 s2, s14, 6
	s_add_u32 s2, s2, 0x134a0200
	s_add_u32 s40, s47, s2
	s_addc_u32 s41, s48, 0
	s_add_u32 s2, s40, 0x0
	s_addc_u32 s3, s41, 0
	global_store_short v135, v114, s[2:3]
	s_add_u32 s2, s40, 0x10
	s_addc_u32 s3, s41, 0
	global_store_short v135, v115, s[2:3]
	s_add_u32 s2, s40, 0x20
	s_addc_u32 s3, s41, 0
	global_store_short v135, v116, s[2:3]
	s_add_u32 s2, s40, 0x30
	s_addc_u32 s3, s41, 0
	global_store_short v135, v117, s[2:3]
	s_add_u32 s2, s40, 0x80
	s_addc_u32 s3, s41, 0
	global_store_short v135, v118, s[2:3]
	s_add_u32 s2, s40, 0x90
	s_addc_u32 s3, s41, 0
	global_store_short v135, v119, s[2:3]
	s_add_u32 s2, s40, 0xa0
	s_addc_u32 s3, s41, 0
	global_store_short v135, v120, s[2:3]
	s_add_u32 s2, s40, 0xb0
	s_addc_u32 s3, s41, 0
	global_store_short v135, v121, s[2:3]
	s_add_u32 s2, s40, 0x400
	s_addc_u32 s3, s41, 0
	global_store_short v135, v122, s[2:3]
	s_add_u32 s2, s40, 0x410
	s_addc_u32 s3, s41, 0
	global_store_short v135, v123, s[2:3]
	s_add_u32 s2, s40, 0x420
	s_addc_u32 s3, s41, 0
	global_store_short v135, v124, s[2:3]
	s_add_u32 s2, s40, 0x430
	s_addc_u32 s3, s41, 0
	global_store_short v135, v125, s[2:3]
	s_add_u32 s2, s40, 0x480
	s_addc_u32 s3, s41, 0
	global_store_short v135, v126, s[2:3]
	s_add_u32 s2, s40, 0x490
	s_addc_u32 s3, s41, 0
	global_store_short v135, v127, s[2:3]
	s_add_u32 s2, s40, 0x4a0
	s_addc_u32 s3, s41, 0
	global_store_short v135, v128, s[2:3]
	s_add_u32 s2, s40, 0x4b0
	s_addc_u32 s3, s41, 0
	global_store_short v135, v129, s[2:3]
	s_add_u32 s2, s40, 0x800
	s_addc_u32 s3, s41, 0
	global_store_short v135, v82, s[2:3]
	s_add_u32 s2, s40, 0x810
	s_addc_u32 s3, s41, 0
	global_store_short v135, v83, s[2:3]
	s_add_u32 s2, s40, 0x820
	s_addc_u32 s3, s41, 0
	global_store_short v135, v84, s[2:3]
	s_add_u32 s2, s40, 0x830
	s_addc_u32 s3, s41, 0
	global_store_short v135, v85, s[2:3]
	s_add_u32 s2, s40, 0x880
	s_addc_u32 s3, s41, 0
	global_store_short v135, v86, s[2:3]
	s_add_u32 s2, s40, 0x890
	s_addc_u32 s3, s41, 0
	global_store_short v135, v87, s[2:3]
	s_add_u32 s2, s40, 0x8a0
	s_addc_u32 s3, s41, 0
	global_store_short v135, v88, s[2:3]
	s_add_u32 s2, s40, 0x8b0
	s_addc_u32 s3, s41, 0
	global_store_short v135, v89, s[2:3]
	s_add_u32 s2, s40, 0xc00
	s_addc_u32 s3, s41, 0
	global_store_short v135, v90, s[2:3]
	s_add_u32 s2, s40, 0xc10
	s_addc_u32 s3, s41, 0
	global_store_short v135, v91, s[2:3]
	s_add_u32 s2, s40, 0xc20
	s_addc_u32 s3, s41, 0
	global_store_short v135, v92, s[2:3]
	s_add_u32 s2, s40, 0xc30
	s_addc_u32 s3, s41, 0
	global_store_short v135, v93, s[2:3]
	s_add_u32 s2, s40, 0xc80
	s_addc_u32 s3, s41, 0
	global_store_short v135, v94, s[2:3]
	s_add_u32 s2, s40, 0xc90
	s_addc_u32 s3, s41, 0
	global_store_short v135, v95, s[2:3]
	s_add_u32 s2, s40, 0xca0
	s_addc_u32 s3, s41, 0
	global_store_short v135, v96, s[2:3]
	s_add_u32 s2, s40, 0xcb0
	s_addc_u32 s3, s41, 0
	global_store_short v135, v97, s[2:3]
	s_add_u32 s2, s40, 0x1000
	s_addc_u32 s3, s41, 0
	global_store_short v135, v50, s[2:3]
	s_add_u32 s2, s40, 0x1010
	s_addc_u32 s3, s41, 0
	global_store_short v135, v51, s[2:3]
	s_add_u32 s2, s40, 0x1020
	s_addc_u32 s3, s41, 0
	global_store_short v135, v52, s[2:3]
	s_add_u32 s2, s40, 0x1030
	s_addc_u32 s3, s41, 0
	global_store_short v135, v53, s[2:3]
	s_add_u32 s2, s40, 0x1080
	s_addc_u32 s3, s41, 0
	global_store_short v135, v54, s[2:3]
	s_add_u32 s2, s40, 0x1090
	s_addc_u32 s3, s41, 0
	global_store_short v135, v55, s[2:3]
	s_add_u32 s2, s40, 0x10a0
	s_addc_u32 s3, s41, 0
	global_store_short v135, v56, s[2:3]
	s_add_u32 s2, s40, 0x10b0
	s_addc_u32 s3, s41, 0
	global_store_short v135, v57, s[2:3]
	s_add_u32 s2, s40, 0x1400
	s_addc_u32 s3, s41, 0
	global_store_short v135, v58, s[2:3]
	s_add_u32 s2, s40, 0x1410
	s_addc_u32 s3, s41, 0
	global_store_short v135, v59, s[2:3]
	s_add_u32 s2, s40, 0x1420
	s_addc_u32 s3, s41, 0
	global_store_short v135, v60, s[2:3]
	s_add_u32 s2, s40, 0x1430
	s_addc_u32 s3, s41, 0
	global_store_short v135, v61, s[2:3]
	s_add_u32 s2, s40, 0x1480
	s_addc_u32 s3, s41, 0
	global_store_short v135, v62, s[2:3]
	s_add_u32 s2, s40, 0x1490
	s_addc_u32 s3, s41, 0
	global_store_short v135, v63, s[2:3]
	s_add_u32 s2, s40, 0x14a0
	s_addc_u32 s3, s41, 0
	global_store_short v135, v64, s[2:3]
	s_add_u32 s2, s40, 0x14b0
	s_addc_u32 s3, s41, 0
	global_store_short v135, v65, s[2:3]
	s_add_u32 s2, s40, 0x1800
	s_addc_u32 s3, s41, 0
	global_store_short v135, v18, s[2:3]
	s_add_u32 s2, s40, 0x1810
	s_addc_u32 s3, s41, 0
	global_store_short v135, v19, s[2:3]
	s_add_u32 s2, s40, 0x1820
	s_addc_u32 s3, s41, 0
	global_store_short v135, v20, s[2:3]
	s_add_u32 s2, s40, 0x1830
	s_addc_u32 s3, s41, 0
	global_store_short v135, v21, s[2:3]
	s_add_u32 s2, s40, 0x1880
	s_addc_u32 s3, s41, 0
	global_store_short v135, v22, s[2:3]
	s_add_u32 s2, s40, 0x1890
	s_addc_u32 s3, s41, 0
	global_store_short v135, v23, s[2:3]
	s_add_u32 s2, s40, 0x18a0
	s_addc_u32 s3, s41, 0
	global_store_short v135, v24, s[2:3]
	s_add_u32 s2, s40, 0x18b0
	s_addc_u32 s3, s41, 0
	global_store_short v135, v25, s[2:3]
	s_add_u32 s2, s40, 0x1c00
	s_addc_u32 s3, s41, 0
	global_store_short v135, v26, s[2:3]
	s_add_u32 s2, s40, 0x1c10
	s_addc_u32 s3, s41, 0
	global_store_short v135, v27, s[2:3]
	s_add_u32 s2, s40, 0x1c20
	s_addc_u32 s3, s41, 0
	global_store_short v135, v28, s[2:3]
	s_add_u32 s2, s40, 0x1c30
	s_addc_u32 s3, s41, 0
	global_store_short v135, v29, s[2:3]
	s_add_u32 s2, s40, 0x1c80
	s_addc_u32 s3, s41, 0
	global_store_short v135, v30, s[2:3]
	s_add_u32 s2, s40, 0x1c90
	s_addc_u32 s3, s41, 0
	global_store_short v135, v31, s[2:3]
	s_add_u32 s2, s40, 0x1ca0
	s_addc_u32 s3, s41, 0
	global_store_short v135, v32, s[2:3]
	s_add_u32 s2, s40, 0x1cb0
	s_addc_u32 s3, s41, 0
	global_store_short v135, v33, s[2:3]

;   __device__ __forceinline__ const float* x() const { return (const float*)(const __attribute__((address_space(1))) float*)kp[0]; }
;   __device__ __forceinline__ half_t* u() const { return (half_t*)(ws() + OFF_u); }
; __device__ __forceinline__ void dsa_item(const KP& p, int b, int tile, char* smem) {
;   const int t0 = tile * 16;
;   int tid = threadIdx.x;
;   asm volatile("" : "+v"(tid));
;   const int lane = tid & 63, wid = tid >> 6;
;   uint32_t* hist = (uint32_t*)smem;
;   unsigned long long* cand = (unsigned long long*)(smem + 16384);
;   unsigned short* sel = (unsigned short*)(smem + 32768);
;   unsigned long long* pfx = (unsigned long long*)(smem + 40960);
;   unsigned long long* tkey = pfx + 16;
;   int* need = (int*)(tkey + 16);
;   int* state = need + 16;
;   int* cnt = state + 16;
;   int* ccnt = cnt + 16;
;   int* pf16 = ccnt + 16;
;   int* ovf = pf16 + 16;
;   int* nrem = ovf + 16;
;   int* fastf = nrem + 8;
;   uint32_t* h1w = (uint32_t*)(smem + 43008);
;   float* pbuf = (float*)smem + wid * 2048;
;   const half_t* ub = p.u() + (size_t)b * SEQ * NU;
;   const int mytok = lane & 15, hq = lane >> 4;
;   const int myt = t0 + mytok;
.LBB0_601:
	s_and_b64 vcc, exec, s[2:3]
	s_cbranch_vccz .LBB0_594
	s_and_b32 s2, s7, 3
	s_lshl_b32 s3, s17, 16
	s_lshl_b32 s50, s2, 11
	s_and_b32 s3, s3, 0x40000
	s_lshl_b32 s2, s2, 8
	s_and_b32 s14, s6, 7
	s_or_b32 s15, s18, 0xfffffbe0
	s_lshl_b32 s12, s18, 2
	v_readlane_b32 s13, v252, 35
	s_add_u32 s52, s13, s12
	v_readlane_b32 s13, v252, 36
	s_addc_u32 s53, s13, 0
	v_readlane_b32 s30, v252, 37
	v_readlane_b32 s31, v252, 38
	s_add_u32 s0, s30, s12
	s_addc_u32 s1, s31, 0
	s_mov_b32 s13, s15
	v_writelane_b32 v252, s0, 59
	s_and_b32 s15, s8, 3
	s_and_b32 s31, s8, 1
	v_writelane_b32 v252, s1, 60
	s_lshl_b32 s30, s15, 15
	s_lshl_b32 s0, s15, 7
	s_lshl_b32 s19, 2, s15
	s_lshl_b32 s70, s31, 13
	s_bfe_u32 s38, s8, 0x10002
	s_bitcmp1_b32 s8, 2
	v_writelane_b32 v252, s0, 61
	s_cselect_b64 s[0:1], -1, 0
	s_lshl_b32 s8, s8, 7
	s_and_b32 s71, s8, 0x180
	v_writelane_b32 v252, s0, 62
	s_cmp_eq_u32 s38, 0
	s_movk_i32 s8, 0x1980
	v_writelane_b32 v252, s1, 63
	s_cselect_b32 s0, 0x1900, s8
	s_movk_i32 s8, 0x58
	v_writelane_b32 v251, s0, 0
	s_cselect_b32 s0, 0x48, s8
	s_lshl_b32 s8, s18, 3
	s_and_b32 s8, s8, 48
	v_writelane_b32 v251, s0, 1
	s_or_b32 s0, s8, 0xffffff00
	v_writelane_b32 v251, s0, 2
	s_lshl_b32 s8, s15, 8
	v_readlane_b32 s0, v252, 39
	s_add_u32 s40, s0, s8
	v_readlane_b32 s1, v252, 40
	s_addc_u32 s41, s1, 0
	v_writelane_b32 v251, s40, 3
	v_readlane_b32 s15, v252, 41
	s_mul_i32 s31, s31, 0x7400000
	v_writelane_b32 v251, s41, 4
	s_add_u32 s40, s15, s30
	v_readlane_b32 s15, v252, 42
	s_addc_u32 s41, s15, 0
	v_writelane_b32 v251, s40, 5
	v_readlane_b32 s15, v252, 43
	s_nop 0
	v_writelane_b32 v251, s41, 6
	s_add_u32 s40, s15, s8
	v_readlane_b32 s8, v252, 44
	s_addc_u32 s41, s8, 0
	s_add_u32 s78, s0, s31
	s_addc_u32 s79, s1, 0
	s_cmp_lg_u32 s31, 0
	s_cselect_b32 s8, 0x80000, 0
	s_add_u32 s8, s8, 0x134a0200
	s_add_u32 s8, s0, s8
	s_addc_u32 s15, s1, 0
	v_writelane_b32 v251, s8, 20
	v_writelane_b32 v251, s15, 21
	s_lshl_b32 s8, s38, 18
	v_readlane_b32 s15, v252, 47
	s_add_u32 s80, s15, s8
	v_readlane_b32 s8, v252, 48
	s_addc_u32 s81, s8, 0
	s_lshl_b32 s8, s38, 8
	v_readlane_b32 s15, v252, 49
	s_add_u32 s82, s15, s8
	v_readlane_b32 s8, v252, 50
	s_addc_u32 s83, s8, 0
	s_add_u32 s84, s0, s2
	s_addc_u32 s85, s1, 0
	s_or_b32 s0, s14, 0xfffffbe0
	v_readlane_b32 s8, v252, 55
	s_add_u32 s86, s8, s2
	v_readlane_b32 s2, v252, 56
	s_addc_u32 s87, s2, 0
	v_readlane_b32 s2, v252, 57
	v_writelane_b32 v251, s40, 7
	s_add_u32 s88, s2, s3
	v_readlane_b32 s2, v252, 58
	v_writelane_b32 v251, s41, 8
	s_addc_u32 s89, s2, 0
	v_writelane_b32 v251, s0, 9
	s_branch .LBB0_605

; __device__ __forceinline__ void dsa_item(const KP& p, int b, int tile, char* smem) {
;     ...
;   auto loadk = [&](int kt, h8* a) __attribute__((always_inline)) {
; #pragma unroll
;     for (int i = 0; i < 2; ++i)
;       a[i] = *(const h8*)(ub + (size_t)(kt * 32 + i * 16 + (lane & 15)) * NU + C_IK + hq * 8);
;   };
;     ...
;       const unsigned long long mypfx = pfx[mytok];
;       const bool act = state[mytok] == 1 && fastf[mytok] == 0;
;       h8 na[2];
;       if (wid < nkt) loadk(wid, na);
.LBB0_778:
	s_mov_b64 s[0:1], s[52:53]
	s_mov_b32 s12, s50
	s_or_b64 exec, exec, s[2:3]
	s_sub_i32 s2, 0x2010, s30
	v_ashrrev_i32_e32 v135, 6, v129
	s_lshr_b32 s68, s2, 5
	v_lshl_or_b32 v125, v135, 5, v157
	v_cmp_le_i32_e64 s[42:43], s68, v135
	v_cmp_gt_i32_e64 s[40:41], s68, v135
	v_mov_b32_e32 v46, 0
	v_lshlrev_b32_e32 v126, 1, v0
	v_or_b32_e32 v0, 16, v125
	v_mov_b32_e32 v47, 0
	v_mov_b32_e32 v48, 0
	v_mov_b32_e32 v49, 0
	v_mov_b32_e32 v42, 0
	v_mov_b32_e32 v43, 0
	v_mov_b32_e32 v44, 0
	v_mov_b32_e32 v45, 0
	s_and_saveexec_b64 s[2:3], s[40:41]
	s_cbranch_execz .LBB0_780
	v_mov_b64_e32 v[38:39], s[78:79]
	v_mad_i64_i32 v[40:41], s[14:15], v125, s5, v[38:39]
	v_mov_b32_e32 v127, v1
	v_lshl_add_u64 v[40:41], v[40:41], 0, v[126:127]
	v_add_co_u32_e32 v40, vcc, 0x3000, v40
	v_mad_i64_i32 v[38:39], s[14:15], v0, s5, v[38:39]
	s_nop 0
	v_addc_co_u32_e32 v41, vcc, 0, v41, vcc
	v_lshl_add_u64 v[38:39], v[38:39], 0, v[126:127]
	v_add_co_u32_e32 v38, vcc, 0x3000, v38
	s_nop 1
	v_addc_co_u32_e32 v39, vcc, 0, v39, vcc
	v_readlane_b32 s14, v251, 20
	v_readlane_b32 s15, v251, 21
	v_add_lshl_u32 v40, v126, v157, 4
	v_lshrrev_b32_e32 v41, 4, v125
	v_lshl_add_u32 v40, v41, 10, v40
	s_nop 4
	global_load_dwordx4 v[46:49], v40, s[14:15]
	global_load_dwordx4 v[42:45], v40, s[14:15] offset:1024

; __device__ __forceinline__ void dsa_item(const KP& p, int b, int tile, char* smem) {
;     ...
;       for (int kt = wid; kt < nkt; kt += 4) {
;         h8 ca[2];
; #pragma unroll
;         for (int i = 0; i < 2; ++i) ca[i] = na[i];
;         loadk(kt + 4 < nkt ? kt + 4 : kt, na);
;         float sc[8];
;         scores(ca, sc);
;         if (act) {
; #pragma unroll
;           for (int q = 0; q < 8; ++q) {
;             const int key = kt * 32 + (q >> 2) * 16 + 4 * hq + (q & 3);
;             if (key <= myt) {
;               if (level < 2) {
;                 const uint32_t u32 = skey(sc[q]);
;                 if (level == 0) {
;                   const uint32_t b8 = u32 >> 24;
;                   atomicAdd(&hist[mytok * 256 + (int)b8], 1u);
;                   if (fillx) {
;                     const uint32_t ix = b8 - 0xBEu;
;                     if (ix < 3u) {
;                       const uint32_t e16 = (ix * 16u + (uint32_t)mytok) * 256u + ((u32 >> 16) & 255u);
;                       atomicAdd(&h1w[e16 >> 1], (e16 & 1u) ? 65536u : 1u);
;                     }
;                   }
;                 } else if ((u32 >> 24) == (uint32_t)mypfx) atomicAdd(&hist[mytok * 256 + (int)((u32 >> 16) & 255u)], 1u);
.LBB0_783:
	v_mfma_f32_16x16x32_f16 v[50:53], v[46:49], v[38:41], 0
	v_mov_b32_e32 v127, v1
	v_mfma_f32_16x16x32_f16 v[86:89], v[46:49], v[34:37], v[50:53]
	v_mfma_f32_16x16x32_f16 v[90:93], v[46:49], v[26:29], 0
	v_mfma_f32_16x16x32_f16 v[94:97], v[46:49], v[2:5], 0
	v_mfma_f32_16x16x32_f16 v[98:101], v[46:49], v[6:9], 0
	v_mfma_f32_16x16x32_f16 v[102:105], v[46:49], v[10:13], 0
	v_mfma_f32_16x16x32_f16 v[106:109], v[46:49], v[14:17], 0
	v_mfma_f32_16x16x32_f16 v[110:113], v[46:49], v[18:21], 0
	v_mfma_f32_16x16x32_f16 v[114:117], v[46:49], v[22:25], 0
	v_mfma_f32_16x16x32_f16 v[118:121], v[46:49], v[30:33], 0
	v_mfma_f32_16x16x32_f16 v[46:49], v[42:45], v[38:41], 0
	v_mfma_f32_16x16x32_f16 v[54:57], v[42:45], v[34:37], v[46:49]
	v_mfma_f32_16x16x32_f16 v[58:61], v[42:45], v[26:29], 0
	s_nop 5
	v_mov_b32_e32 v46, v148
	v_add_u32_e32 v148, 4, v46
	v_cmp_gt_i32_e32 vcc, s68, v148
	v_mfma_f32_16x16x32_f16 v[62:65], v[42:45], v[2:5], 0
	s_nop 0
	v_cndmask_b32_e32 v46, v46, v148, vcc
	v_lshl_or_b32 v50, v46, 5, v157
	v_mov_b64_e32 v[46:47], s[78:79]
	v_mad_i64_i32 v[48:49], s[2:3], v50, s5, v[46:47]
	v_lshl_add_u64 v[48:49], v[48:49], 0, v[126:127]
	v_or_b32_e32 v50, 16, v50
	v_add_co_u32_e32 v48, vcc, s23, v48
	v_mad_i64_i32 v[46:47], s[2:3], v50, s5, v[46:47]
	s_nop 0
	v_addc_co_u32_e32 v49, vcc, 0, v49, vcc
	v_lshl_add_u64 v[46:47], v[46:47], 0, v[126:127]
	v_add_co_u32_e32 v50, vcc, s23, v46
	v_mfma_f32_16x16x32_f16 v[66:69], v[42:45], v[6:9], 0
	s_nop 0
	v_addc_co_u32_e32 v51, vcc, 0, v47, vcc
	v_readlane_b32 s2, v251, 20
	v_readlane_b32 s3, v251, 21
	v_add_lshl_u32 v50, v126, v157, 4
	v_lshl_add_u32 v50, v148, 11, v50
	s_nop 4
	global_load_dwordx4 v[46:49], v50, s[2:3]
	global_load_dwordx4 v[50:53], v50, s[2:3] offset:1024
	v_mfma_f32_16x16x32_f16 v[70:73], v[42:45], v[10:13], 0
	v_cmp_le_i32_e32 vcc, s68, v148
	v_mfma_f32_16x16x32_f16 v[74:77], v[42:45], v[14:17], 0
	v_mfma_f32_16x16x32_f16 v[78:81], v[42:45], v[18:21], 0
	v_mfma_f32_16x16x32_f16 v[82:85], v[42:45], v[22:25], 0
	v_mfma_f32_16x16x32_f16 v[42:45], v[42:45], v[30:33], 0
	s_and_saveexec_b64 s[2:3], s[48:49]
	s_cbranch_execz .LBB0_782
	v_subrev_u32_e32 v127, 19, v144
	v_cmp_le_i32_e64 s[44:45], v127, v133
	s_and_saveexec_b64 s[54:55], s[44:45]
	s_cbranch_execz .LBB0_787
	v_fma_f32 v86, |v90|, v128, v86
	v_fma_f32 v86, |v94|, v130, v86
	v_fma_f32 v86, |v98|, v132, v86
	v_fma_f32 v86, |v102|, v134, v86
	v_fma_f32 v86, |v106|, v136, v86
	v_fma_f32 v86, |v110|, v138, v86
	v_fma_f32 v86, |v114|, v140, v86
	v_fma_f32 v86, |v118|, v142, v86
	v_add_f32_e32 v86, 0, v86
	v_not_b32_e32 v90, v86
	v_or_b32_e32 v94, 0x80000000, v86
	v_cmp_gt_i32_e64 s[44:45], 0, v86
	s_nop 1
	v_cndmask_b32_e64 v86, v94, v90, s[44:45]
	v_lshrrev_b32_e32 v90, 24, v86
	v_lshl_add_u32 v94, v90, 2, v147
	ds_add_u32 v94, v226
	v_add_u32_e32 v90, 0xffffff42, v90
	v_cmp_gt_u32_e64 s[44:45], 3, v90
	s_and_b64 exec, exec, s[44:45]
	s_cbranch_execz .LBB0_787
	v_lshlrev_b32_e32 v90, 12, v90
	v_and_b32_sdwa v94, v86, s24 dst_sel:DWORD dst_unused:UNUSED_PAD src0_sel:WORD_1 src1_sel:DWORD
	v_and_b32_e32 v86, 0x10000, v86
	v_or3_b32 v90, v90, v94, v123
	v_cmp_eq_u32_e64 s[44:45], 0, v86
	v_lshlrev_b32_e32 v90, 1, v90
	s_nop 0
	v_cndmask_b32_e64 v86, v236, 1, s[44:45]
	ds_add_u32 v90, v86 offset:43008

; __device__ __forceinline__ void dsa_item(const KP& p, int b, int tile, char* smem) {
;     ...
;   if (tid < 16) fastf[tid] = 0;
;   __syncthreads();
;   {
;     const int st0 = state[mytok];
;     const unsigned long long mytk = tkey[mytok];
;     const unsigned long long myp16 = pfx[mytok];
;     h8 na[2];
;     if (wid < nkt) loadk(wid, na);
.LBB0_1074:
	s_or_b64 exec, exec, s[66:67]
	s_waitcnt lgkmcnt(0)
	s_barrier
	s_and_saveexec_b64 s[2:3], s[46:47]
	ds_write_b32 v124, v1 offset:41632
	s_or_b64 exec, exec, s[2:3]
	v_add_u32_e32 v42, 0xa000, v143
	s_waitcnt lgkmcnt(0)
	s_barrier
	ds_read_b32 v54, v145 offset:41280
	ds_read2_b64 v[42:45], v42 offset1:16
	s_and_saveexec_b64 s[2:3], s[40:41]
	s_cbranch_execz .LBB0_1078
	v_mov_b64_e32 v[46:47], s[78:79]
	v_mad_i64_i32 v[48:49], s[14:15], v125, s5, v[46:47]
	v_mov_b32_e32 v127, v1
	v_lshl_add_u64 v[48:49], v[48:49], 0, v[126:127]
	v_add_co_u32_e32 v48, vcc, 0x3000, v48
	v_mad_i64_i32 v[46:47], s[14:15], v0, s5, v[46:47]
	s_nop 0
	v_addc_co_u32_e32 v49, vcc, 0, v49, vcc
	v_lshl_add_u64 v[46:47], v[46:47], 0, v[126:127]
	v_add_co_u32_e32 v46, vcc, 0x3000, v46
	s_nop 1
	v_addc_co_u32_e32 v47, vcc, 0, v47, vcc
	v_readlane_b32 s14, v251, 20
	v_readlane_b32 s15, v251, 21
	v_add_lshl_u32 v48, v126, v157, 4
	v_lshrrev_b32_e32 v49, 4, v125
	v_lshl_add_u32 v48, v49, 10, v48
	s_nop 4
	global_load_dwordx4 v[50:53], v48, s[14:15]
	global_load_dwordx4 v[46:49], v48, s[14:15] offset:1024

; __device__ __forceinline__ void dsa_item(const KP& p, int b, int tile, char* smem) {
;     ...
;     for (int kt = wid; kt < nkt; kt += 4) {
;       h8 ca[2];
; #pragma unroll
;       for (int i = 0; i < 2; ++i) ca[i] = na[i];
;       loadk(kt + 4 < nkt ? kt + 4 : kt, na);
;       float sc[8];
;       scores(ca, sc);
; #pragma unroll
;       for (int q = 0; q < 8; ++q) {
;         const int key = kt * 32 + (q >> 2) * 16 + 4 * hq + (q & 3);
;         if (key <= myt) {
;           const uint32_t u32 = skey(sc[q]);
;           bool take, isc = false;
;           if (st0 == 0) take = (((unsigned long long)u32 << 16) | (unsigned long long)(8191 - key)) >= mytk;
;           else {
;             const uint32_t p16 = u32 >> 16;
;             take = p16 > (uint32_t)myp16;
;             isc = p16 == (uint32_t)myp16;
;           }
;           if (take) {
;             const int pos = atomicAdd(&cnt[mytok], 1);
;             if (pos < 256) sel[mytok * 256 + pos] = (unsigned short)key;
;           } else if (isc) {
;             const int pos = atomicAdd(&ccnt[mytok], 1);
;             if (pos < DSA_CAP) cand[mytok * 128 + pos] = ((unsigned long long)u32 << 16) | (unsigned long long)(8191 - key);
;           }
;         }
.LBB0_1081:
	s_waitcnt vmcnt(0)
	v_mov_b64_e32 v[88:89], v[48:49]
	v_mov_b64_e32 v[86:87], v[46:47]
	v_mfma_f32_16x16x32_f16 v[54:57], v[50:53], v[38:41], 0
	v_mov_b32_e32 v0, v162
	v_add_u32_e32 v162, 4, v0
	v_cmp_gt_i32_e32 vcc, s68, v162
	v_mfma_f32_16x16x32_f16 v[46:49], v[86:89], v[38:41], 0
	v_mov_b32_e32 v127, v1
	v_cndmask_b32_e32 v0, v0, v162, vcc
	v_lshl_or_b32 v0, v0, 5, v157
	v_mfma_f32_16x16x32_f16 v[90:93], v[50:53], v[34:37], v[54:57]
	v_cmp_le_i32_e64 s[60:61], v160, v133
	v_mfma_f32_16x16x32_f16 v[54:57], v[86:89], v[34:37], v[46:49]
	s_nop 2
	v_mov_b64_e32 v[46:47], s[78:79]
	v_mad_i64_i32 v[48:49], s[2:3], v0, s5, v[46:47]
	v_lshl_add_u64 v[48:49], v[48:49], 0, v[126:127]
	v_or_b32_e32 v0, 16, v0
	v_add_co_u32_e32 v48, vcc, s23, v48
	v_mad_i64_i32 v[46:47], s[2:3], v0, s5, v[46:47]
	s_nop 0
	v_addc_co_u32_e32 v49, vcc, 0, v49, vcc
	v_lshl_add_u64 v[46:47], v[46:47], 0, v[126:127]
	v_add_co_u32_e32 v46, vcc, s23, v46
	v_mfma_f32_16x16x32_f16 v[94:97], v[50:53], v[26:29], 0
	s_nop 0
	v_addc_co_u32_e32 v47, vcc, 0, v47, vcc
	v_cmp_le_i32_e32 vcc, s68, v162
	v_mfma_f32_16x16x32_f16 v[98:101], v[50:53], v[2:5], 0
	v_mfma_f32_16x16x32_f16 v[102:105], v[50:53], v[6:9], 0
	v_mfma_f32_16x16x32_f16 v[106:109], v[50:53], v[10:13], 0
	v_mfma_f32_16x16x32_f16 v[110:113], v[50:53], v[14:17], 0
	v_mfma_f32_16x16x32_f16 v[114:117], v[50:53], v[18:21], 0
	v_mfma_f32_16x16x32_f16 v[118:121], v[50:53], v[22:25], 0
	v_mfma_f32_16x16x32_f16 v[122:125], v[50:53], v[30:33], 0
	v_readlane_b32 s2, v251, 20
	v_readlane_b32 s3, v251, 21
	v_add_lshl_u32 v48, v126, v157, 4
	v_lshl_add_u32 v48, v162, 11, v48
	s_nop 4
	global_load_dwordx4 v[50:53], v48, s[2:3]
	global_load_dwordx4 v[46:49], v48, s[2:3] offset:1024
	v_mfma_f32_16x16x32_f16 v[58:61], v[86:89], v[26:29], 0
	v_mfma_f32_16x16x32_f16 v[62:65], v[86:89], v[2:5], 0
	v_mfma_f32_16x16x32_f16 v[66:69], v[86:89], v[6:9], 0
	v_mfma_f32_16x16x32_f16 v[70:73], v[86:89], v[10:13], 0
	v_mfma_f32_16x16x32_f16 v[74:77], v[86:89], v[14:17], 0
	v_mfma_f32_16x16x32_f16 v[78:81], v[86:89], v[18:21], 0
	v_mfma_f32_16x16x32_f16 v[82:85], v[86:89], v[22:25], 0
	v_mfma_f32_16x16x32_f16 v[86:89], v[86:89], v[30:33], 0
	s_and_saveexec_b64 s[2:3], s[60:61]
	s_cbranch_execz .LBB0_1094
	v_fma_f32 v0, |v94|, v128, v90
	v_fma_f32 v0, |v98|, v130, v0
	v_fma_f32 v0, |v102|, v132, v0
	v_fma_f32 v0, |v106|, v134, v0
	v_fma_f32 v0, |v110|, v136, v0
	v_fma_f32 v0, |v114|, v138, v0
	v_fma_f32 v0, |v118|, v140, v0
	v_fma_f32 v0, |v122|, v142, v0
	v_add_f32_e32 v0, 0, v0
	v_not_b32_e32 v90, v0
	v_or_b32_e32 v94, 0x80000000, v0
	v_cmp_gt_i32_e64 s[60:61], 0, v0
	s_nop 1
	v_cndmask_b32_e64 v0, v94, v90, s[60:61]
	s_and_saveexec_b64 s[14:15], s[46:47]
	s_xor_b64 s[14:15], exec, s[14:15]
	v_cmp_gt_u32_sdwa s[30:31], v0, v42 src0_sel:WORD_1 src1_sel:DWORD
	v_cmp_eq_u32_sdwa s[66:67], v0, v42 src0_sel:WORD_1 src1_sel:DWORD
	s_andn2_saveexec_b64 s[14:15], s[14:15]
	v_lshlrev_b64 v[164:165], 16, v[0:1]
	v_or_b32_e32 v164, v164, v161
	v_cmp_ge_u64_e64 s[60:61], v[164:165], v[44:45]
	s_andn2_b64 s[30:31], s[30:31], exec
	s_and_b64 s[60:61], s[60:61], exec
	s_andn2_b64 s[66:67], s[66:67], exec
	s_or_b64 s[30:31], s[30:31], s[60:61]
	s_or_b64 exec, exec, s[14:15]
	s_xor_b64 s[14:15], s[30:31], -1
	s_and_saveexec_b64 s[30:31], s[14:15]
	s_xor_b64 s[30:31], exec, s[30:31]
	s_cbranch_execz .LBB0_1091
	s_and_saveexec_b64 s[14:15], s[66:67]
	s_cbranch_execz .LBB0_1090
	ds_add_rtn_u32 v90, v145, v226 offset:41408
	s_waitcnt lgkmcnt(0)
	v_cmp_gt_i32_e64 s[60:61], s33, v90
	s_and_b64 exec, exec, s[60:61]
	v_lshlrev_b64 v[164:165], 16, v[0:1]
	v_or_b32_e32 v164, v164, v161
	v_lshl_add_u32 v0, v90, 3, v147
	ds_write_b64 v0, v[164:165] offset:16384
